# post1 row loop: xor-8/4/2/1 steps of the two wave-wide sums via DPP adds instead of ds_bpermute round trips (bit-identical order)
# baseline (speedup 1.0000x reference)
; DEV unsigned pack2(float a, float b) { f32x2 v = {a, b}; return __builtin_bit_cast(unsigned, __builtin_convertvector(v, bf2_t)); }
; DEV float bflo(unsigned u) { return __uint_as_float(u << 16); }
; DEV float bfhi(unsigned u) { return __uint_as_float(u & 0xffff0000u); }
; DEV void phase_post1(const Params& p) {
;     ...
;     {
;       uint2 u = *(const uint2*)(pr + lane * 4);
;       float a0 = bflo(u.x), a1 = bfhi(u.x), a2 = bflo(u.y), a3 = bfhi(u.y);
;       float ss = wave_sum(a0 * a0 + a1 * a1 + a2 * a2 + a3 * a3);
;       float rinv = rsqrtf(ss * (1.f / 256.f) + 1e-6f);
;       float4 g4 = ((const float4*)qg)[lane];
;       uint2 r; r.x = pack2(a0 * rinv * g4.x, a1 * rinv * g4.y); r.y = pack2(a2 * rinv * g4.z, a3 * rinv * g4.w);
;       *(uint2*)(QN + (size_t)row * 256 + lane * 4) = r;
;     }
;     {
;       unsigned u = *(const unsigned*)(pr + 256 + lane * 2);
;       float a0 = bflo(u), a1 = bfhi(u);
;       float ss = wave_sum(a0 * a0 + a1 * a1);
;       float rinv = rsqrtf(ss * (1.f / 128.f) + 1e-6f);
;       float2 g2 = ((const float2*)kvg)[lane];
;       *(unsigned*)(KVN + (size_t)row * 128 + lane * 2) = pack2(a0 * rinv * g2.x, a1 * rinv * g2.y);
;     }
;     if (lane < 16) {
;       unsigned u = *(const unsigned*)(pr + 384 + lane * 2);
;       float x0 = bflo(u), x1 = bfhi(u);
;       int b, pos;
;       if (row < MM) {
;         b = row >> 13; int t = row & 8191; pos = 256 + t;
;         float c = rc[t * 16 + lane], s = rs[t * 16 + lane];
;         float y0 = x0 * c - x1 * s, y1 = x0 * s + x1 * c; x0 = y0; x1 = y1;
.LBB0_1026:
	v_mov_b64_e32 v[2:3], s[2:3]
	s_movk_i32 s12, 0xc00
	v_mad_i64_i32 v[2:3], s[12:13], v10, s12, v[2:3]
	v_lshl_add_u64 v[4:5], v[2:3], 0, v[0:1]
	global_load_dwordx2 v[4:5], v[4:5], off
	s_mov_b32 s12, 0x800000
	v_ashrrev_i32_e32 v11, 31, v10
	s_waitcnt vmcnt(0)
	v_lshlrev_b32_e32 v8, 16, v4
	v_and_b32_e32 v9, 0xffff0000, v4
	v_lshlrev_b32_e32 v28, 16, v5
	v_and_b32_e32 v29, 0xffff0000, v5
	global_load_dwordx4 v[4:7], v[14:15], off
	v_pk_mul_f32 v[38:39], v[8:9], v[8:9]
	v_pk_mul_f32 v[36:37], v[28:29], v[28:29]
	v_add_f32_e32 v13, v38, v39
	v_add_f32_e32 v13, v13, v36
	v_add_f32_e32 v13, v37, v13
	ds_bpermute_b32 v25, v30, v13
	s_waitcnt lgkmcnt(0)
	v_add_f32_e32 v13, v13, v25
	ds_bpermute_b32 v25, v31, v13
	s_waitcnt lgkmcnt(0)
	v_add_f32_e32 v13, v13, v25
	s_nop 1
	v_add_f32_dpp v13, v13, v13 row_ror:8 row_mask:0xf bank_mask:0xf
	v_mov_b32_e32 v25, v13
	s_nop 0
	v_add_f32_dpp v25, v13, v13 row_shl:4 row_mask:0xf bank_mask:0x5
	v_add_f32_dpp v25, v13, v13 row_shr:4 row_mask:0xf bank_mask:0xa
	s_nop 1
	v_add_f32_dpp v25, v25, v25 quad_perm:[2,3,0,1] row_mask:0xf bank_mask:0xf
	s_nop 1
	v_add_f32_dpp v13, v25, v25 quad_perm:[1,0,3,2] row_mask:0xf bank_mask:0xf
	v_fmamk_f32 v13, v13, 0x3b800000, v211
	v_cmp_gt_f32_e32 vcc, s12, v13
	v_mul_f32_e32 v25, 0x4b800000, v13
	s_nop 0
	v_cndmask_b32_e32 v13, v13, v25, vcc
	v_rsq_f32_e32 v13, v13
	s_nop 0
	v_mul_f32_e32 v25, 0x45800000, v13
	v_cndmask_b32_e32 v36, v13, v25, vcc
	v_pk_mul_f32 v[8:9], v[36:37], v[8:9] op_sel_hi:[0,1]
	v_mov_b32_e32 v25, v1
	s_waitcnt vmcnt(0)
	v_pk_mul_f32 v[4:5], v[4:5], v[8:9]
	v_pk_mul_f32 v[8:9], v[36:37], v[28:29] op_sel_hi:[0,1]
	v_pk_mul_f32 v[6:7], v[6:7], v[8:9]
	v_cvt_pk_bf16_f32 v4, v4, v5
	v_cvt_pk_bf16_f32 v5, v6, v7
	v_lshlrev_b64 v[6:7], 9, v[10:11]
	v_lshl_add_u64 v[6:7], v[16:17], 0, v[6:7]
	global_store_dwordx2 v[6:7], v[4:5], off
	v_lshl_add_u64 v[4:5], v[2:3], 0, v[24:25]
	global_load_dword v7, v[4:5], off offset:512
	global_load_dwordx2 v[28:29], v[18:19], off
	s_waitcnt vmcnt(1)
	v_lshlrev_b32_e32 v6, 16, v7
	v_and_b32_e32 v7, 0xffff0000, v7
	v_pk_mul_f32 v[8:9], v[6:7], v[6:7]
	s_nop 0
	v_add_f32_e32 v8, v8, v9
	ds_bpermute_b32 v9, v30, v8
	s_waitcnt lgkmcnt(0)
	v_add_f32_e32 v8, v8, v9
	ds_bpermute_b32 v9, v31, v8
	s_waitcnt lgkmcnt(0)
	v_add_f32_e32 v8, v8, v9
	s_nop 1
	v_add_f32_dpp v8, v8, v8 row_ror:8 row_mask:0xf bank_mask:0xf
	v_mov_b32_e32 v9, v8
	s_nop 0
	v_add_f32_dpp v9, v8, v8 row_shl:4 row_mask:0xf bank_mask:0x5
	v_add_f32_dpp v9, v8, v8 row_shr:4 row_mask:0xf bank_mask:0xa
	s_nop 1
	v_add_f32_dpp v9, v9, v9 quad_perm:[2,3,0,1] row_mask:0xf bank_mask:0xf
	s_nop 1
	v_add_f32_dpp v8, v9, v9 quad_perm:[1,0,3,2] row_mask:0xf bank_mask:0xf
	v_fmamk_f32 v8, v8, 0x3c000000, v211
	v_cmp_gt_f32_e32 vcc, s12, v8
	v_mul_f32_e32 v9, 0x4b800000, v8
	s_nop 0
	v_cndmask_b32_e32 v8, v8, v9, vcc
	v_rsq_f32_e32 v8, v8
	s_nop 0
	v_mul_f32_e32 v9, 0x45800000, v8
	v_cndmask_b32_e32 v8, v8, v9, vcc
	v_pk_mul_f32 v[6:7], v[8:9], v[6:7] op_sel_hi:[0,1]
	s_waitcnt vmcnt(0)
	v_pk_mul_f32 v[6:7], v[28:29], v[6:7]
	s_nop 0
	v_cvt_pk_bf16_f32 v8, v6, v7
	v_lshlrev_b64 v[6:7], 8, v[10:11]
	v_lshl_add_u64 v[6:7], v[20:21], 0, v[6:7]
	global_store_dword v[6:7], v8, off
	s_and_saveexec_b64 s[12:13], s[38:39]
	s_cbranch_execz .LBB0_1025
	global_load_dword v4, v[4:5], off offset:768
	v_cmp_lt_i32_e32 vcc, s23, v10
	s_waitcnt vmcnt(0)
	v_lshlrev_b32_e32 v6, 16, v4
	v_and_b32_e32 v7, 0xffff0000, v4
	s_and_saveexec_b64 s[14:15], vcc
	s_xor_b64 s[14:15], exec, s[14:15]
	v_add_u32_e32 v4, 0xffffc000, v10
	v_lshrrev_b32_e32 v5, 8, v4
	v_and_b32_e32 v4, 0xff, v10
	s_andn2_saveexec_b64 s[14:15], s[14:15]
	s_cbranch_execz .LBB0_1024
	v_and_b32_e32 v4, 0x1fff, v10
	v_lshl_or_b32 v5, v4, 6, v12
	global_load_dword v8, v5, s[8:9]
	global_load_dword v28, v5, s[6:7]
	v_ashrrev_i32_e32 v5, 13, v10
	v_add_u32_e32 v4, 0x100, v4
	s_waitcnt vmcnt(1)
	v_pk_mul_f32 v[8:9], v[8:9], v[6:7] op_sel:[0,1] op_sel_hi:[0,0]
	s_waitcnt vmcnt(0)
	v_pk_mul_f32 v[36:37], v[28:29], v[6:7] op_sel_hi:[0,1]
	v_pk_fma_f32 v[6:7], v[28:29], v[6:7], v[8:9] op_sel_hi:[0,1,1]
	v_sub_f32_e32 v6, v36, v8
	s_branch .LBB0_1024
